# GU and residual GEMM loops: LDS-DMA loads in scalar-base form
# baseline (speedup 1.0000x reference)
;     __device__ __forceinline__ void stage_rs(const Unit& u, int tid, int wid) const { stage_rs_lds(SS, rsl, u, tid, wid); }
;     __device__ __forceinline__ void stage_rs(const Unit& u, int tid, int wid) const { stage_rs_lds(SS, rsl, u, tid, wid); }
; #define PG8_STAGE(bufoff, gbase, voff) do { _Pragma("unroll") for (int _i = 0; _i < 2; ++_i) \
;         __builtin_amdgcn_global_load_lds((const unsigned*)((const char*)(gbase) + (voff)[_i]), (PG8_LAS unsigned*)(lds + (bufoff) + ldsw + _i * 8192), 16, 0, 0); } while (0)
; #define PG8_LDA(dst, b, h) do { _Pragma("unroll") for (int m = 0; m < 4; ++m) _Pragma("unroll") for (int k = 0; k < 2; ++k) dst[m][k] = *(const PG8_LAS bf16x8*)(lds + PG8_SA(b, h) + aoff + m * 2048 + k * 1024); } while (0)
; #define PG8_LDB(dst, b, h) do { _Pragma("unroll") for (int n = 0; n < 2; ++n) _Pragma("unroll") for (int k = 0; k < 2; ++k) dst[n][k] = *(const PG8_LAS bf16x8*)(lds + PG8_SB(b, h) + boff + n * 2048 + k * 1024); } while (0)
; #define PG8_WAIT_V(n) asm volatile("s_waitcnt vmcnt(" #n ")" ::: "memory")
; template <class Epi, class Sched, bool ALIGN_EPI = false, bool SP2 = false>
; __device__ __forceinline__ void gemm_phase(PG8_LAS unsigned char* lds, const Gemm g, const Sched& S, const Epi& E, const int tid) {
;     ...
;             const bool last = (t == nt - 2);
;             if constexpr (Epi::RS_LDS) { if (t == nt - 4) E.stage_rs(cur, tid, wid); }
;             if constexpr (Epi::PREFETCH) { if (t >= nt - 8) E.prefetch(cur, lds, tid, wid, (t - (nt - 8)) >> 1); }
;             const char* a1 = cA + (size_t)(t + 1) * kstep;
;             const char* a2 = last ? nA : cA + (size_t)(t + 2) * kstep; const char* b2 = last ? nB : cB + (size_t)(t + 2) * kstep;
;             const char* a3 = a2 + kstep; const char* b3 = b2 + kstep;
;             if (last && has_next) S.a_ready(nxt);
;             if constexpr (SP2) {
;             PG8_LDB(B0, 0, 0); PG8_LDB(B1, 0, 1); PG8_SCHED; PG8_LDA(At, 0, 0); PG8_STAGE(PG8_SA(1, 1), a1 + hstep, voffA);
;             PG8_WAIT_V(8); PG8_WAIT_L(0); PG8_BAR; PG8_MMA(0, 0, At, B0); PG8_MMA(0, 1, At, B1); PG8_BAR; PG8_SCHED;
;             PG8_LDA(At, 0, 1); PG8_STAGE(PG8_SB(0, 0), b2, voffB); PG8_STAGE(PG8_SB(0, 1), b2 + hstep, voffB); PG8_STAGE(PG8_SA(0, 0), a2, voffA);
;             PG8_WAIT_V(8); PG8_WAIT_L(0); PG8_BAR; PG8_MMA(1, 0, At, B0); PG8_MMA(1, 1, At, B1); PG8_BAR; PG8_SCHED;
.LBB0_618:
	s_add_i32 s85, s70, 2
	s_add_u32 s38, s68, 0x80
	s_addc_u32 s39, s69, 0
	s_add_i32 s59, 0, 0x10000
	s_cmp_eq_u32 s81, s70
	s_cselect_b32 s71, s11, s39
	s_cselect_b32 s70, s10, s38
	s_cselect_b32 s39, s67, s51
	s_cselect_b32 s38, s66, s50
	s_add_i32 s86, 0, 0x14000
	v_add_u32_e32 v142, s59, v205
	v_add_u32_e32 v180, s86, v205
	ds_read_b128 v[130:133], v142
	ds_read_b128 v[134:137], v142 offset:1024
	ds_read_b128 v[138:141], v142 offset:2048
	ds_read_b128 v[142:145], v142 offset:3072
	ds_read_b128 v[146:149], v180
	ds_read_b128 v[150:153], v180 offset:1024
	ds_read_b128 v[176:179], v180 offset:2048
	ds_read_b128 v[180:183], v180 offset:3072
	s_add_i32 m0, s73, 0xc000
	ds_read_b128 v[184:187], v207
	ds_read_b128 v[188:191], v207 offset:1024
	ds_read_b128 v[208:211], v207 offset:2048
	ds_read_b128 v[212:215], v207 offset:3072
	ds_read_b128 v[216:219], v207 offset:4096
	ds_read_b128 v[220:223], v207 offset:5120
	ds_read_b128 v[224:227], v207 offset:6144
	ds_read_b128 v[228:231], v207 offset:7168
	global_load_lds_dwordx4 v172, s[68:69]
	s_add_i32 m0, s73, 0xe000
	s_nop 0
	global_load_lds_dwordx4 v174, s[68:69]
	s_waitcnt vmcnt(8)
	s_waitcnt lgkmcnt(0)
	s_setprio 1
	s_barrier
	v_mfma_f32_16x16x32_bf16 v[126:129], v[130:133], v[184:187], v[126:129]
	v_mfma_f32_16x16x32_bf16 v[122:125], v[138:141], v[184:187], v[122:125]
	v_mfma_f32_16x16x32_bf16 v[110:113], v[130:133], v[208:211], v[110:113]
	v_mfma_f32_16x16x32_bf16 v[106:109], v[138:141], v[208:211], v[106:109]
	v_mfma_f32_16x16x32_bf16 v[94:97], v[130:133], v[216:219], v[94:97]
	v_mfma_f32_16x16x32_bf16 v[90:93], v[138:141], v[216:219], v[90:93]
	v_mfma_f32_16x16x32_bf16 v[78:81], v[130:133], v[224:227], v[78:81]
	v_mfma_f32_16x16x32_bf16 v[74:77], v[138:141], v[224:227], v[74:77]
	v_mfma_f32_16x16x32_bf16 v[126:129], v[134:137], v[188:191], v[126:129]
	v_mfma_f32_16x16x32_bf16 v[122:125], v[142:145], v[188:191], v[122:125]
	v_mfma_f32_16x16x32_bf16 v[110:113], v[134:137], v[212:215], v[110:113]
	v_mfma_f32_16x16x32_bf16 v[106:109], v[142:145], v[212:215], v[106:109]
	v_mfma_f32_16x16x32_bf16 v[94:97], v[134:137], v[220:223], v[94:97]
	v_mfma_f32_16x16x32_bf16 v[90:93], v[142:145], v[220:223], v[90:93]
	v_mfma_f32_16x16x32_bf16 v[78:81], v[134:137], v[228:231], v[78:81]
	v_mfma_f32_16x16x32_bf16 v[74:77], v[142:145], v[228:231], v[74:77]
	v_mfma_f32_16x16x32_bf16 v[118:121], v[146:149], v[184:187], v[118:121]
	v_mfma_f32_16x16x32_bf16 v[114:117], v[176:179], v[184:187], v[114:117]
	v_mfma_f32_16x16x32_bf16 v[102:105], v[146:149], v[208:211], v[102:105]
	v_mfma_f32_16x16x32_bf16 v[98:101], v[176:179], v[208:211], v[98:101]
	v_mfma_f32_16x16x32_bf16 v[86:89], v[146:149], v[216:219], v[86:89]
	v_mfma_f32_16x16x32_bf16 v[82:85], v[176:179], v[216:219], v[82:85]
	v_mfma_f32_16x16x32_bf16 v[70:73], v[146:149], v[224:227], v[70:73]
	v_mfma_f32_16x16x32_bf16 v[66:69], v[176:179], v[224:227], v[66:69]
	v_mfma_f32_16x16x32_bf16 v[118:121], v[150:153], v[188:191], v[118:121]
	v_mfma_f32_16x16x32_bf16 v[114:117], v[180:183], v[188:191], v[114:117]
	v_mfma_f32_16x16x32_bf16 v[102:105], v[150:153], v[212:215], v[102:105]
	v_mfma_f32_16x16x32_bf16 v[98:101], v[180:183], v[212:215], v[98:101]
	v_mfma_f32_16x16x32_bf16 v[86:89], v[150:153], v[220:223], v[86:89]
	v_mfma_f32_16x16x32_bf16 v[82:85], v[180:183], v[220:223], v[82:85]
	v_mfma_f32_16x16x32_bf16 v[70:73], v[150:153], v[228:231], v[70:73]
	v_mfma_f32_16x16x32_bf16 v[66:69], v[180:183], v[228:231], v[66:69]
	s_setprio 0
	s_barrier
	s_add_i32 s59, s59, s72
	s_mov_b64 s[90:91], s[38:39]
	s_mov_b32 m0, s59
	ds_read_b128 v[184:187], v207 offset:16384
	ds_read_b128 v[188:191], v207 offset:17408
	ds_read_b128 v[208:211], v207 offset:18432
	ds_read_b128 v[212:215], v207 offset:19456
	ds_read_b128 v[216:219], v207 offset:20480
	ds_read_b128 v[220:223], v207 offset:21504
	ds_read_b128 v[224:227], v207 offset:22528
	ds_read_b128 v[228:231], v207 offset:23552
	global_load_lds_dwordx4 v0, s[38:39]
	s_add_i32 m0, s59, 0x2000
	s_add_i32 s59, s86, s72
	global_load_lds_dwordx4 v166, s[38:39]
	s_add_u32 s38, s38, s14
	s_addc_u32 s39, s39, 0
	s_mov_b32 m0, s59
	s_nop 0
	global_load_lds_dwordx4 v0, s[38:39]
	s_add_i32 m0, s59, 0x2000
	s_nop 0
	global_load_lds_dwordx4 v166, s[38:39]
	s_mov_b32 m0, s73
	s_nop 0
	global_load_lds_dwordx4 v170, s[70:71]
	s_mov_b32 m0, s74
	s_nop 0
	global_load_lds_dwordx4 v168, s[70:71]
	s_waitcnt vmcnt(8)
	s_waitcnt lgkmcnt(0)
	s_setprio 1
	s_barrier
	v_mfma_f32_16x16x32_bf16 v[62:65], v[130:133], v[184:187], v[62:65]
	v_mfma_f32_16x16x32_bf16 v[58:61], v[138:141], v[184:187], v[58:61]
	v_mfma_f32_16x16x32_bf16 v[46:49], v[130:133], v[208:211], v[46:49]
	v_mfma_f32_16x16x32_bf16 v[42:45], v[138:141], v[208:211], v[42:45]
	v_mfma_f32_16x16x32_bf16 v[30:33], v[130:133], v[216:219], v[30:33]
	v_mfma_f32_16x16x32_bf16 v[26:29], v[138:141], v[216:219], v[26:29]
	v_mfma_f32_16x16x32_bf16 v[14:17], v[130:133], v[224:227], v[14:17]
	v_mfma_f32_16x16x32_bf16 v[10:13], v[138:141], v[224:227], v[10:13]
	v_mfma_f32_16x16x32_bf16 v[62:65], v[134:137], v[188:191], v[62:65]
	v_mfma_f32_16x16x32_bf16 v[58:61], v[142:145], v[188:191], v[58:61]
	v_mfma_f32_16x16x32_bf16 v[46:49], v[134:137], v[212:215], v[46:49]
	v_mfma_f32_16x16x32_bf16 v[42:45], v[142:145], v[212:215], v[42:45]
	v_mfma_f32_16x16x32_bf16 v[30:33], v[134:137], v[220:223], v[30:33]
	v_mfma_f32_16x16x32_bf16 v[26:29], v[142:145], v[220:223], v[26:29]
	v_mfma_f32_16x16x32_bf16 v[14:17], v[134:137], v[228:231], v[14:17]
	v_mfma_f32_16x16x32_bf16 v[10:13], v[142:145], v[228:231], v[10:13]
	v_mfma_f32_16x16x32_bf16 v[54:57], v[146:149], v[184:187], v[54:57]
	v_mfma_f32_16x16x32_bf16 v[50:53], v[176:179], v[184:187], v[50:53]
	v_mfma_f32_16x16x32_bf16 v[38:41], v[146:149], v[208:211], v[38:41]
	v_mfma_f32_16x16x32_bf16 v[34:37], v[176:179], v[208:211], v[34:37]
	v_mfma_f32_16x16x32_bf16 v[22:25], v[146:149], v[216:219], v[22:25]
	v_mfma_f32_16x16x32_bf16 v[18:21], v[176:179], v[216:219], v[18:21]
	v_mfma_f32_16x16x32_bf16 v[6:9], v[146:149], v[224:227], v[6:9]
	v_mfma_f32_16x16x32_bf16 v[2:5], v[176:179], v[224:227], v[2:5]
	v_mfma_f32_16x16x32_bf16 v[54:57], v[150:153], v[188:191], v[54:57]
	v_mfma_f32_16x16x32_bf16 v[50:53], v[180:183], v[188:191], v[50:53]
	v_mfma_f32_16x16x32_bf16 v[38:41], v[150:153], v[212:215], v[38:41]
	v_mfma_f32_16x16x32_bf16 v[34:37], v[180:183], v[212:215], v[34:37]
	v_mfma_f32_16x16x32_bf16 v[22:25], v[150:153], v[220:223], v[22:25]
	v_mfma_f32_16x16x32_bf16 v[18:21], v[180:183], v[220:223], v[18:21]
	v_mfma_f32_16x16x32_bf16 v[6:9], v[150:153], v[228:231], v[6:9]
	v_mfma_f32_16x16x32_bf16 v[2:5], v[180:183], v[228:231], v[2:5]
	s_setprio 0
	s_barrier
; #define PG8_STAGE(bufoff, gbase, voff) do { _Pragma("unroll") for (int _i = 0; _i < 2; ++_i) \
;         __builtin_amdgcn_global_load_lds((const unsigned*)((const char*)(gbase) + (voff)[_i]), (PG8_LAS unsigned*)(lds + (bufoff) + ldsw + _i * 8192), 16, 0, 0); } while (0)
; #define PG8_LDA(dst, b, h) do { _Pragma("unroll") for (int m = 0; m < 4; ++m) _Pragma("unroll") for (int k = 0; k < 2; ++k) dst[m][k] = *(const PG8_LAS bf16x8*)(lds + PG8_SA(b, h) + aoff + m * 2048 + k * 1024); } while (0)
; #define PG8_LDB(dst, b, h) do { _Pragma("unroll") for (int n = 0; n < 2; ++n) _Pragma("unroll") for (int k = 0; k < 2; ++k) dst[n][k] = *(const PG8_LAS bf16x8*)(lds + PG8_SB(b, h) + boff + n * 2048 + k * 1024); } while (0)
; #define PG8_MMA(ai, bj, At, Bt) do { __builtin_amdgcn_s_setprio(1); _Pragma("unroll") for (int m = 0; m < 4; ++m) _Pragma("unroll") for (int n = 0; n < 2; ++n) _Pragma("unroll") for (int k = 0; k < 2; ++k) \
;         acc[ai][bj][m][n] = __builtin_amdgcn_mfma_f32_16x16x32_bf16(Bt[n][k], At[m][k], acc[ai][bj][m][n], 0, 0, 0); __builtin_amdgcn_s_setprio(0); } while (0)
; #define PG8_WAIT_V(n) asm volatile("s_waitcnt vmcnt(" #n ")" ::: "memory")
; #define PG8_WAIT_L(n) asm volatile("s_waitcnt lgkmcnt(" #n ")" ::: "memory")
; #define PG8_BAR __builtin_amdgcn_s_barrier()
; #define PG8_SCHED __builtin_amdgcn_sched_barrier(0)
; template <class Epi, class Sched, bool ALIGN_EPI = false, bool SP2 = false>
; __device__ __forceinline__ void gemm_phase(PG8_LAS unsigned char* lds, const Gemm g, const Sched& S, const Epi& E, const int tid) {
;     ...
;             PG8_LDB(B0, 1, 0); PG8_LDB(B1, 1, 1); PG8_SCHED; PG8_LDA(At, 1, 0); PG8_STAGE(PG8_SA(0, 1), a2 + hstep, voffA);
;             PG8_WAIT_V(8); PG8_WAIT_L(0); PG8_BAR; PG8_MMA(0, 0, At, B0); PG8_MMA(0, 1, At, B1); PG8_BAR; PG8_SCHED;
;             PG8_LDA(At, 1, 1); PG8_STAGE(PG8_SB(1, 0), b3, voffB); PG8_STAGE(PG8_SB(1, 1), b3 + hstep, voffB); PG8_STAGE(PG8_SA(1, 0), a3, voffA);
;             PG8_WAIT_V(8); PG8_WAIT_L(0); PG8_BAR; PG8_MMA(1, 0, At, B0); PG8_MMA(1, 1, At, B1); PG8_BAR; PG8_SCHED;
;     ...
;         if constexpr (ALIGN_EPI) { if (wr == 0) PG8_BAR; }
	s_add_i32 s59, 0, 0x18000
	s_add_i32 s86, 0, 0x1c000
	v_add_u32_e32 v142, s59, v205
	v_add_u32_e32 v180, s86, v205
	ds_read_b128 v[130:133], v142
	ds_read_b128 v[134:137], v142 offset:1024
	ds_read_b128 v[138:141], v142 offset:2048
	ds_read_b128 v[142:145], v142 offset:3072
	ds_read_b128 v[146:149], v180
	ds_read_b128 v[150:153], v180 offset:1024
	ds_read_b128 v[176:179], v180 offset:2048
	ds_read_b128 v[180:183], v180 offset:3072
	s_add_u32 s38, s70, s14
	s_addc_u32 s39, s71, 0
	s_mov_b32 m0, s75
	ds_read_b128 v[184:187], v207 offset:32768
	ds_read_b128 v[188:191], v207 offset:33792
	ds_read_b128 v[208:211], v207 offset:34816
	ds_read_b128 v[212:215], v207 offset:35840
	ds_read_b128 v[216:219], v207 offset:36864
	ds_read_b128 v[220:223], v207 offset:37888
	ds_read_b128 v[224:227], v207 offset:38912
	ds_read_b128 v[228:231], v207 offset:39936
	global_load_lds_dwordx4 v170, s[38:39]
	s_mov_b32 m0, s76
	s_nop 0
	global_load_lds_dwordx4 v168, s[38:39]
	s_waitcnt vmcnt(8)
	s_waitcnt lgkmcnt(0)
	s_setprio 1
	s_barrier
	v_mfma_f32_16x16x32_bf16 v[126:129], v[130:133], v[184:187], v[126:129]
	v_mfma_f32_16x16x32_bf16 v[122:125], v[138:141], v[184:187], v[122:125]
	v_mfma_f32_16x16x32_bf16 v[110:113], v[130:133], v[208:211], v[110:113]
	v_mfma_f32_16x16x32_bf16 v[106:109], v[138:141], v[208:211], v[106:109]
	v_mfma_f32_16x16x32_bf16 v[94:97], v[130:133], v[216:219], v[94:97]
	v_mfma_f32_16x16x32_bf16 v[90:93], v[138:141], v[216:219], v[90:93]
	v_mfma_f32_16x16x32_bf16 v[78:81], v[130:133], v[224:227], v[78:81]
	v_mfma_f32_16x16x32_bf16 v[74:77], v[138:141], v[224:227], v[74:77]
	v_mfma_f32_16x16x32_bf16 v[126:129], v[134:137], v[188:191], v[126:129]
	v_mfma_f32_16x16x32_bf16 v[122:125], v[142:145], v[188:191], v[122:125]
	v_mfma_f32_16x16x32_bf16 v[110:113], v[134:137], v[212:215], v[110:113]
	v_mfma_f32_16x16x32_bf16 v[106:109], v[142:145], v[212:215], v[106:109]
	v_mfma_f32_16x16x32_bf16 v[94:97], v[134:137], v[220:223], v[94:97]
	v_mfma_f32_16x16x32_bf16 v[90:93], v[142:145], v[220:223], v[90:93]
	v_mfma_f32_16x16x32_bf16 v[78:81], v[134:137], v[228:231], v[78:81]
	v_mfma_f32_16x16x32_bf16 v[74:77], v[142:145], v[228:231], v[74:77]
	v_mfma_f32_16x16x32_bf16 v[118:121], v[146:149], v[184:187], v[118:121]
	v_mfma_f32_16x16x32_bf16 v[114:117], v[176:179], v[184:187], v[114:117]
	v_mfma_f32_16x16x32_bf16 v[102:105], v[146:149], v[208:211], v[102:105]
	v_mfma_f32_16x16x32_bf16 v[98:101], v[176:179], v[208:211], v[98:101]
	v_mfma_f32_16x16x32_bf16 v[86:89], v[146:149], v[216:219], v[86:89]
	v_mfma_f32_16x16x32_bf16 v[82:85], v[176:179], v[216:219], v[82:85]
	v_mfma_f32_16x16x32_bf16 v[70:73], v[146:149], v[224:227], v[70:73]
	v_mfma_f32_16x16x32_bf16 v[66:69], v[176:179], v[224:227], v[66:69]
	v_mfma_f32_16x16x32_bf16 v[118:121], v[150:153], v[188:191], v[118:121]
	v_mfma_f32_16x16x32_bf16 v[114:117], v[180:183], v[188:191], v[114:117]
	v_mfma_f32_16x16x32_bf16 v[102:105], v[150:153], v[212:215], v[102:105]
	v_mfma_f32_16x16x32_bf16 v[98:101], v[180:183], v[212:215], v[98:101]
	v_mfma_f32_16x16x32_bf16 v[86:89], v[150:153], v[220:223], v[86:89]
	v_mfma_f32_16x16x32_bf16 v[82:85], v[180:183], v[220:223], v[82:85]
	v_mfma_f32_16x16x32_bf16 v[70:73], v[150:153], v[228:231], v[70:73]
	v_mfma_f32_16x16x32_bf16 v[66:69], v[180:183], v[228:231], v[66:69]
	s_setprio 0
	s_barrier
	s_add_i32 s38, s59, s72
	s_add_u32 s90, s90, 0x80
	s_addc_u32 s91, s91, 0
	s_mov_b32 m0, s38
	ds_read_b128 v[184:187], v207 offset:49152
	ds_read_b128 v[188:191], v207 offset:50176
	ds_read_b128 v[208:211], v207 offset:51200
	ds_read_b128 v[212:215], v207 offset:52224
	ds_read_b128 v[216:219], v207 offset:53248
	ds_read_b128 v[220:223], v207 offset:54272
	ds_read_b128 v[224:227], v207 offset:55296
	ds_read_b128 v[228:231], v207 offset:56320
	global_load_lds_dwordx4 v0, s[90:91]
	s_add_i32 m0, s38, 0x2000
	s_add_i32 s38, s86, s72
	global_load_lds_dwordx4 v166, s[90:91]
	s_add_u32 s90, s90, s14
	s_addc_u32 s91, s91, 0
	s_mov_b32 m0, s38
	s_nop 0
	global_load_lds_dwordx4 v0, s[90:91]
	s_add_i32 m0, s38, 0x2000
	s_add_u32 s92, s70, 0x80
	s_addc_u32 s93, s71, 0
	global_load_lds_dwordx4 v166, s[90:91]
	s_mov_b32 m0, s79
	s_nop 0
	global_load_lds_dwordx4 v170, s[92:93]
	s_mov_b32 m0, s80
	s_nop 0
	global_load_lds_dwordx4 v168, s[92:93]
	s_waitcnt vmcnt(8)
	s_waitcnt lgkmcnt(0)
	s_setprio 1
	s_barrier
	v_mfma_f32_16x16x32_bf16 v[62:65], v[130:133], v[184:187], v[62:65]
	v_mfma_f32_16x16x32_bf16 v[58:61], v[138:141], v[184:187], v[58:61]
	v_mfma_f32_16x16x32_bf16 v[46:49], v[130:133], v[208:211], v[46:49]
	v_mfma_f32_16x16x32_bf16 v[42:45], v[138:141], v[208:211], v[42:45]
	v_mfma_f32_16x16x32_bf16 v[30:33], v[130:133], v[216:219], v[30:33]
	v_mfma_f32_16x16x32_bf16 v[26:29], v[138:141], v[216:219], v[26:29]
	v_mfma_f32_16x16x32_bf16 v[14:17], v[130:133], v[224:227], v[14:17]
	v_mfma_f32_16x16x32_bf16 v[10:13], v[138:141], v[224:227], v[10:13]
	v_mfma_f32_16x16x32_bf16 v[62:65], v[134:137], v[188:191], v[62:65]
	v_mfma_f32_16x16x32_bf16 v[58:61], v[142:145], v[188:191], v[58:61]
	v_mfma_f32_16x16x32_bf16 v[46:49], v[134:137], v[212:215], v[46:49]
	v_mfma_f32_16x16x32_bf16 v[42:45], v[142:145], v[212:215], v[42:45]
	v_mfma_f32_16x16x32_bf16 v[30:33], v[134:137], v[220:223], v[30:33]
	v_mfma_f32_16x16x32_bf16 v[26:29], v[142:145], v[220:223], v[26:29]
	v_mfma_f32_16x16x32_bf16 v[14:17], v[134:137], v[228:231], v[14:17]
	v_mfma_f32_16x16x32_bf16 v[10:13], v[142:145], v[228:231], v[10:13]
	v_mfma_f32_16x16x32_bf16 v[54:57], v[146:149], v[184:187], v[54:57]
	v_mfma_f32_16x16x32_bf16 v[50:53], v[176:179], v[184:187], v[50:53]
	v_mfma_f32_16x16x32_bf16 v[38:41], v[146:149], v[208:211], v[38:41]
	v_mfma_f32_16x16x32_bf16 v[34:37], v[176:179], v[208:211], v[34:37]
	v_mfma_f32_16x16x32_bf16 v[22:25], v[146:149], v[216:219], v[22:25]
	v_mfma_f32_16x16x32_bf16 v[18:21], v[176:179], v[216:219], v[18:21]
	v_mfma_f32_16x16x32_bf16 v[6:9], v[146:149], v[224:227], v[6:9]
	v_mfma_f32_16x16x32_bf16 v[2:5], v[176:179], v[224:227], v[2:5]
	v_mfma_f32_16x16x32_bf16 v[54:57], v[150:153], v[188:191], v[54:57]
	v_mfma_f32_16x16x32_bf16 v[50:53], v[180:183], v[188:191], v[50:53]
	v_mfma_f32_16x16x32_bf16 v[38:41], v[150:153], v[212:215], v[38:41]
	v_mfma_f32_16x16x32_bf16 v[34:37], v[180:183], v[212:215], v[34:37]
	v_mfma_f32_16x16x32_bf16 v[22:25], v[150:153], v[220:223], v[22:25]
	v_mfma_f32_16x16x32_bf16 v[18:21], v[180:183], v[220:223], v[18:21]
	v_mfma_f32_16x16x32_bf16 v[6:9], v[150:153], v[228:231], v[6:9]
	v_mfma_f32_16x16x32_bf16 v[2:5], v[180:183], v[228:231], v[2:5]
	s_setprio 0
	s_barrier
	s_add_u32 s68, s68, 0x100
	s_addc_u32 s69, s69, 0
	s_add_u32 s50, s50, 0x100
	s_addc_u32 s51, s51, 0
	s_cmp_ge_u32 s85, s78
	s_mov_b32 s70, s85
	s_cbranch_scc0 .LBB0_618
	s_and_b64 vcc, exec, s[22:23]
	s_cbranch_vccz .LBB0_621
	s_barrier
